# layer-0 w_in GEMM main tiles: XCDs 6 decode positions apart instead of 12 (rotation inside each XCD's 192 positions), rest as v45
# speedup vs baseline: 1.0138x; 1.0089x over previous
.Lgi_sk_rot0:
	s_and_b32 s0, s54, 7
	s_lshr_b32 s1, s54, 3
	s_mul_i32 s57, s0, 186
	s_add_u32 s1, s1, s57
	s_mul_i32 s57, s1, 0x5556
	s_lshr_b32 s57, s57, 22
	s_mul_i32 s57, s57, 192
	s_sub_u32 s1, s1, s57
	s_lshl_b32 s1, s1, 3
	s_or_b32 s57, s1, s0
	s_branch .Lgi_sk_dec
